# v8: redundant second accumulator zeroing per GEMM tile removed
# speedup vs baseline: 1.0504x; 1.0029x over previous
.Latt_u_noS:
	s_add_i32 s49, s49, 1
	s_cmp_gt_u32 s49, s47
	s_cbranch_scc1 .LBB0_44
	s_barrier
	s_branch .Latt_u_loop
	s_nop 0
	s_nop 0
	s_nop 0
	s_nop 0
	s_nop 0
	s_nop 0
	s_nop 0
	s_nop 0
	s_nop 0
	s_nop 0
	s_nop 0
	s_nop 0
	s_nop 0
	s_nop 0
	s_nop 0
	s_nop 0
	s_nop 0
	s_nop 0
	s_nop 0
	s_nop 0
	s_nop 0
	s_nop 0
	s_nop 0
	s_nop 0
	s_nop 0
	s_nop 0
	s_nop 0
	s_nop 0
	s_nop 0
	s_nop 0
	s_nop 0
	s_nop 0
	s_nop 0
	s_nop 0
	s_nop 0
	s_nop 0
	s_nop 0
	s_nop 0
	s_nop 0
	s_nop 0
	s_nop 0
	s_nop 0
	s_nop 0
	s_nop 0
	s_nop 0
	s_nop 0
	s_nop 0
	s_nop 0
	s_nop 0
	s_nop 0
	s_nop 0
	s_nop 0
	s_nop 0
	s_nop 0
	s_nop 0
	s_nop 0
	s_nop 0
	s_nop 0
	s_nop 0
	s_nop 0
	s_nop 0
	s_nop 0
	s_nop 0
	s_nop 0
	s_nop 0
	s_nop 0
	s_nop 0
	s_nop 0
	s_nop 0
	s_nop 0
	s_nop 0
	s_nop 0
	s_nop 0
	s_nop 0
	s_nop 0
	s_nop 0
	s_nop 0
	s_nop 0
	s_nop 0
	s_nop 0
	s_nop 0
	s_nop 0
	s_nop 0
	s_nop 0
	s_nop 0
	s_nop 0
	s_nop 0
	s_nop 0
	s_nop 0
	s_nop 0
	s_nop 0
	s_nop 0
	s_nop 0
	s_nop 0
	s_nop 0
	s_nop 0
	s_nop 0
	s_nop 0
	s_nop 0
	s_nop 0
	s_nop 0
	s_nop 0
	s_nop 0
	s_nop 0
	s_nop 0
	s_nop 0
	s_nop 0
	s_nop 0
	s_nop 0
	s_nop 0
	s_nop 0
	s_nop 0
	s_nop 0
	s_nop 0
	s_nop 0
	s_nop 0
	s_nop 0
	s_nop 0
	s_nop 0
	s_nop 0
	s_nop 0
	s_nop 0
	s_nop 0
	s_nop 0
	s_nop 0
	s_nop 0
	s_nop 0
	s_nop 0
	s_nop 0
	s_nop 0
	s_nop 0
	s_nop 0
	s_nop 0
	s_nop 0
	s_nop 0
	s_nop 0
	s_nop 0
	s_nop 0
	s_nop 0
	s_nop 0
	s_nop 0
	s_nop 0
	s_nop 0
	s_nop 0
	s_nop 0
	s_nop 0
	s_nop 0
	s_nop 0
	s_nop 0
	s_nop 0
	s_nop 0
	s_nop 0
	s_nop 0
	s_nop 0
	s_nop 0
	s_nop 0
	s_nop 0
	s_nop 0
	s_nop 0
	s_nop 0
	s_nop 0
	s_nop 0
	s_nop 0
	s_nop 0
	s_nop 0
	s_nop 0
	s_nop 0
	s_nop 0
	s_nop 0
	s_nop 0
	s_nop 0
	s_nop 0
	s_nop 0
	s_nop 0
	s_nop 0
	s_nop 0
	s_nop 0
	s_nop 0
	s_nop 0
	s_nop 0
	s_nop 0
	s_nop 0
	s_nop 0
	s_nop 0
	s_nop 0
	s_nop 0
	s_nop 0
	s_nop 0
	s_nop 0
	s_nop 0
	s_nop 0
	s_nop 0
	s_nop 0
	s_nop 0
	s_nop 0
	s_nop 0
	s_nop 0
	s_nop 0
	s_nop 0
	s_nop 0
	s_nop 0
	s_nop 0
	s_nop 0
	s_nop 0
	s_nop 0
	s_nop 0
	s_nop 0
	s_nop 0
	s_nop 0
	s_nop 0
	s_nop 0
	s_nop 0
	s_nop 0
	s_nop 0
	s_nop 0
	s_nop 0
	s_nop 0
	s_nop 0
	s_nop 0
	s_nop 0
	s_nop 0
	s_nop 0
	s_nop 0
	s_nop 0
	s_nop 0
	s_nop 0
	s_nop 0
	s_nop 0
	s_nop 0
	s_nop 0
	s_nop 0
	s_nop 0
	s_nop 0
	s_nop 0
	s_nop 0
	s_nop 0
	s_nop 0
	s_nop 0
	s_nop 0
	s_nop 0
	s_nop 0
	s_nop 0
	s_nop 0
	s_nop 0
	s_nop 0
	s_nop 0
	s_nop 0
	s_nop 0
	s_nop 0
	s_nop 0
	s_nop 0
	s_nop 0
	s_nop 0
	s_nop 0
	s_nop 0
	s_nop 0
	s_nop 0
	s_nop 0
	s_nop 0
	s_nop 0
	s_nop 0
	s_nop 0
	s_nop 0
	s_nop 0
	s_nop 0
	s_nop 0
	s_nop 0
	s_nop 0
	s_nop 0
	s_nop 0
	s_nop 0
	s_nop 0
	s_nop 0
	s_nop 0
	s_nop 0
	s_nop 0
	s_nop 0
	s_nop 0
	s_nop 0
	s_nop 0
	s_nop 0
	s_nop 0
	s_nop 0
	s_nop 0
	s_nop 0
	s_nop 0
	s_nop 0
	s_nop 0
	s_nop 0
	s_nop 0
	s_nop 0
	s_nop 0
	s_nop 0
	s_nop 0
	s_nop 0
	s_nop 0
	s_nop 0
	s_nop 0
	s_nop 0
	s_nop 0
	s_nop 0
	s_nop 0
	s_nop 0
	s_nop 0
	s_nop 0
	s_nop 0
	s_nop 0
	s_nop 0
	s_nop 0
	s_nop 0
	s_nop 0
	s_nop 0
	s_nop 0
	s_nop 0
	s_nop 0
	s_nop 0
	s_nop 0
	s_nop 0
	s_nop 0
	s_nop 0
	s_nop 0
	s_nop 0
	s_nop 0
	s_nop 0
	s_nop 0
	s_nop 0
	s_nop 0
	s_nop 0
	s_nop 0
	s_nop 0
	s_nop 0
	s_nop 0
	s_nop 0
	s_nop 0
	s_nop 0
	s_nop 0
	s_nop 0
	s_nop 0
	s_nop 0
	s_nop 0
	s_nop 0
	s_nop 0
	s_nop 0
	s_nop 0
	s_nop 0
	s_nop 0
	s_nop 0
	s_nop 0
	s_nop 0
	s_nop 0
	s_nop 0
	s_nop 0
	s_nop 0
	s_nop 0
	s_nop 0
	s_nop 0
	s_nop 0
	s_nop 0
	s_nop 0
	s_nop 0
	s_nop 0
	s_nop 0
	s_nop 0
	s_nop 0
	s_nop 0
	s_nop 0
	s_nop 0
	s_nop 0
	s_nop 0
	s_nop 0
	s_nop 0
	s_nop 0
	s_nop 0
	s_nop 0
	s_nop 0
	s_nop 0
	s_nop 0
	s_nop 0
	s_nop 0
	s_nop 0
	s_nop 0
	s_nop 0
	s_nop 0
	s_nop 0
	s_nop 0
	s_nop 0
	s_nop 0
	s_nop 0
	s_nop 0
	s_nop 0
	s_nop 0
	s_nop 0
	s_nop 0
	s_nop 0
	s_nop 0
	s_nop 0
	s_nop 0
	s_nop 0
	s_nop 0
	s_nop 0
	s_nop 0
	s_nop 0
	s_nop 0
	s_nop 0
	s_nop 0
	s_nop 0
	s_nop 0
	s_nop 0
	s_nop 0
	s_nop 0
	s_nop 0
	s_nop 0
	s_nop 0
	s_nop 0
	s_nop 0
	s_nop 0
	s_nop 0
	s_nop 0
	s_nop 0
	s_nop 0
	s_nop 0
	s_nop 0
	s_nop 0
	s_nop 0
	s_nop 0
	s_nop 0
	s_nop 0
	s_nop 0

.LBB0_430:
	v_mov_b32_e32 v129, 0
	s_andn2_b64 vcc, exec, s[6:7]
	v_mov_b32_e32 v128, v129
	v_mov_b32_e32 v127, v129
	v_mov_b32_e32 v126, v129
	v_mov_b32_e32 v125, v129
	v_mov_b32_e32 v124, v129
	v_mov_b32_e32 v123, v129
	v_mov_b32_e32 v122, v129
	v_mov_b32_e32 v113, v129
	v_mov_b32_e32 v112, v129
	v_mov_b32_e32 v111, v129
	v_mov_b32_e32 v110, v129
	v_mov_b32_e32 v109, v129
	v_mov_b32_e32 v108, v129
	v_mov_b32_e32 v107, v129
	v_mov_b32_e32 v106, v129
	v_mov_b32_e32 v97, v129
	v_mov_b32_e32 v96, v129
	v_mov_b32_e32 v95, v129
	v_mov_b32_e32 v94, v129
	v_mov_b32_e32 v93, v129
	v_mov_b32_e32 v92, v129
	v_mov_b32_e32 v91, v129
	v_mov_b32_e32 v90, v129
	v_mov_b32_e32 v81, v129
	v_mov_b32_e32 v80, v129
	v_mov_b32_e32 v79, v129
	v_mov_b32_e32 v78, v129
	v_mov_b32_e32 v77, v129
	v_mov_b32_e32 v76, v129
	v_mov_b32_e32 v75, v129
	v_mov_b32_e32 v74, v129
	v_mov_b32_e32 v121, v129
	v_mov_b32_e32 v120, v129
	v_mov_b32_e32 v119, v129
	v_mov_b32_e32 v118, v129
	v_mov_b32_e32 v117, v129
	v_mov_b32_e32 v116, v129
	v_mov_b32_e32 v115, v129
	v_mov_b32_e32 v114, v129
	v_mov_b32_e32 v105, v129
	v_mov_b32_e32 v104, v129
	v_mov_b32_e32 v103, v129
	v_mov_b32_e32 v102, v129
	v_mov_b32_e32 v101, v129
	v_mov_b32_e32 v100, v129
	v_mov_b32_e32 v99, v129
	v_mov_b32_e32 v98, v129
	v_mov_b32_e32 v89, v129
	v_mov_b32_e32 v88, v129
	v_mov_b32_e32 v87, v129
	v_mov_b32_e32 v86, v129
	v_mov_b32_e32 v85, v129
	v_mov_b32_e32 v84, v129
	v_mov_b32_e32 v83, v129
	v_mov_b32_e32 v82, v129
	v_mov_b32_e32 v73, v129
	v_mov_b32_e32 v72, v129
	v_mov_b32_e32 v71, v129
	v_mov_b32_e32 v70, v129
	v_mov_b32_e32 v69, v129
	v_mov_b32_e32 v68, v129
	v_mov_b32_e32 v67, v129
	v_mov_b32_e32 v66, v129
	v_mov_b32_e32 v65, v129
	v_mov_b32_e32 v64, v129
	v_mov_b32_e32 v63, v129
	v_mov_b32_e32 v62, v129
	v_mov_b32_e32 v61, v129
	v_mov_b32_e32 v60, v129
	v_mov_b32_e32 v59, v129
	v_mov_b32_e32 v58, v129
	v_mov_b32_e32 v49, v129
	v_mov_b32_e32 v48, v129
	v_mov_b32_e32 v47, v129
	v_mov_b32_e32 v46, v129
	v_mov_b32_e32 v45, v129
	v_mov_b32_e32 v44, v129
	v_mov_b32_e32 v43, v129
	v_mov_b32_e32 v42, v129
	v_mov_b32_e32 v33, v129
	v_mov_b32_e32 v32, v129
	v_mov_b32_e32 v31, v129
	v_mov_b32_e32 v30, v129
	v_mov_b32_e32 v29, v129
	v_mov_b32_e32 v28, v129
	v_mov_b32_e32 v27, v129
	v_mov_b32_e32 v26, v129
	v_mov_b32_e32 v17, v129
	v_mov_b32_e32 v16, v129
	v_mov_b32_e32 v15, v129
	v_mov_b32_e32 v14, v129
	v_mov_b32_e32 v13, v129
	v_mov_b32_e32 v12, v129
	v_mov_b32_e32 v11, v129
	v_mov_b32_e32 v10, v129
	v_mov_b32_e32 v57, v129
	v_mov_b32_e32 v56, v129
	v_mov_b32_e32 v55, v129
	v_mov_b32_e32 v54, v129
	v_mov_b32_e32 v53, v129
	v_mov_b32_e32 v52, v129
	v_mov_b32_e32 v51, v129
	v_mov_b32_e32 v50, v129
	v_mov_b32_e32 v41, v129
	v_mov_b32_e32 v40, v129
	v_mov_b32_e32 v39, v129
	v_mov_b32_e32 v38, v129
	v_mov_b32_e32 v37, v129
	v_mov_b32_e32 v36, v129
	v_mov_b32_e32 v35, v129
	v_mov_b32_e32 v34, v129
	v_mov_b32_e32 v25, v129
	v_mov_b32_e32 v24, v129
	v_mov_b32_e32 v23, v129
	v_mov_b32_e32 v22, v129
	v_mov_b32_e32 v21, v129
	v_mov_b32_e32 v20, v129
	v_mov_b32_e32 v19, v129
	v_mov_b32_e32 v18, v129
	v_mov_b32_e32 v9, v129
	v_mov_b32_e32 v8, v129
	v_mov_b32_e32 v7, v129
	v_mov_b32_e32 v6, v129
	v_mov_b32_e32 v5, v129
	v_mov_b32_e32 v4, v129
	v_mov_b32_e32 v3, v129
	v_mov_b32_e32 v2, v129
	s_cbranch_vccnz .LBB0_433
	s_add_u32 s46, s74, 0x80
	s_addc_u32 s47, s75, 0
	s_add_u32 s38, s78, 0x100
	s_addc_u32 s39, s79, 0
	s_mov_b32 s41, 0
